# attention softmax: units with nb>=1 apply only the distance test of key tiles 0,1,8,9 (key>=0 and tiles 2..7 tests are always true there); nb==0 units unchanged
# baseline (speedup 1.0000x reference)
.LBB0_1133:
	v_ashrrev_i32_e32 v98, 9, v99
	v_cmp_eq_u32_e32 vcc, 2, v98
	s_mov_b32 s10, 0xff800000
	s_nop 0
	v_cndmask_b32_e64 v0, 0, 4, vcc
	v_cmp_ne_u32_e32 vcc, 1, v98
	s_nop 1
	v_cndmask_b32_e32 v0, 2, v0, vcc
	v_lshrrev_b32_e64 v2, v0, 32
	v_add_u32_e32 v2, -1, v2
	v_bitop3_b32 v2, v2, v99, 31 bitop3:0x80
	v_cmp_eq_u32_e32 vcc, 3, v98
	v_lshlrev_b32_e32 v3, 7, v2
	v_sub_u32_e32 v2, 0x7f, v3
	v_cndmask_b32_e32 v97, v229, v230, vcc
	s_nop 0
	v_readfirstlane_b32 s100, v2
	s_nop 1
	s_cmp_lt_i32 s100, 0
	s_cbranch_scc0 .Lattn_mask_full
	v_cmp_le_u32_e64 s[46:47], v116, v97
	v_cmp_le_u32_e64 s[34:35], v117, v97
	v_cmp_le_u32_e64 s[100:101], v119, v97
	v_cmp_le_u32_e32 vcc, v121, v97
	v_cndmask_b32_e64 v56, v231, v56, s[46:47]
	v_cndmask_b32_e64 v57, v231, v57, s[34:35]
	v_cndmask_b32_e64 v58, v231, v58, s[100:101]
	v_cndmask_b32_e32 v59, v231, v59, vcc
	v_cmp_le_u32_e64 s[46:47], v123, v97
	v_cmp_le_u32_e64 s[34:35], v124, v97
	v_cmp_le_u32_e64 s[100:101], v126, v97
	v_cmp_le_u32_e32 vcc, v128, v97
	v_cndmask_b32_e64 v72, v231, v72, s[46:47]
	v_cndmask_b32_e64 v73, v231, v73, s[34:35]
	v_cndmask_b32_e64 v74, v231, v74, s[100:101]
	v_cndmask_b32_e32 v75, v231, v75, vcc
	v_max3_f32 v200, v56, s10, v57
	v_max3_f32 v200, v200, v58, v59
	v_max3_f32 v200, v200, v72, v73
	v_max3_f32 v200, v200, v74, v75
	v_max3_f32 v200, v200, v88, v89
	v_max3_f32 v200, v200, v90, v91
	v_max3_f32 v200, v200, v84, v85
	v_max3_f32 v200, v200, v86, v87
	v_max3_f32 v200, v200, v80, v81
	v_max3_f32 v200, v200, v82, v83
	v_max3_f32 v200, v200, v76, v77
	v_max3_f32 v200, v200, v78, v79
	v_max3_f32 v200, v200, v64, v65
	v_max3_f32 v200, v200, v66, v67
	v_max3_f32 v200, v200, v68, v69
	v_max3_f32 v200, v200, v70, v71
	v_cmp_le_u32_e64 s[46:47], v172, v97
	v_cmp_le_u32_e64 s[34:35], v173, v97
	v_cmp_le_u32_e64 s[100:101], v175, v97
	v_cmp_le_u32_e32 vcc, v177, v97
	v_cndmask_b32_e64 v60, v231, v60, s[46:47]
	v_cndmask_b32_e64 v201, v231, v61, s[34:35]
	v_cndmask_b32_e32 v202, v231, v63, vcc
	v_max3_f32 v61, v200, v60, v201
	v_cndmask_b32_e64 v200, v231, v62, s[100:101]
	v_cmp_le_u32_e64 s[46:47], v191, v97
	v_cmp_le_u32_e64 s[34:35], v192, v97
	v_cmp_le_u32_e64 s[100:101], v194, v97
	v_cmp_le_u32_e32 vcc, v196, v97
	v_cndmask_b32_e64 v203, v231, v52, s[46:47]
	v_cndmask_b32_e64 v204, v231, v53, s[34:35]
	v_cndmask_b32_e64 v205, v231, v54, s[100:101]
	v_cndmask_b32_e32 v55, v231, v55, vcc
	v_max3_f32 v61, v61, v200, v202
	v_max3_f32 v52, v61, v203, v204
	v_and_b32_e32 v53, 64, v226
	v_max3_f32 v2, v52, v205, v55
	s_branch .Lattn_mask_join
.Lattn_mask_full:
	v_cmp_le_u32_e32 vcc, v116, v97
	v_cmp_gt_i32_e64 s[46:47], v115, v2
	s_and_b64 vcc, vcc, s[46:47]
	v_cndmask_b32_e32 v56, v231, v56, vcc
	v_cmp_le_u32_e32 vcc, v117, v97
	v_cmp_ge_i32_e64 s[46:47], v115, v2
	s_and_b64 vcc, vcc, s[46:47]
	v_cndmask_b32_e32 v57, v231, v57, vcc
	v_cmp_le_u32_e32 vcc, v119, v97
	v_cmp_gt_i32_e64 s[46:47], v118, v2
	s_and_b64 vcc, vcc, s[46:47]
	v_cndmask_b32_e32 v58, v231, v58, vcc
	v_cmp_le_u32_e32 vcc, v121, v97
	v_cmp_gt_i32_e64 s[46:47], v120, v2
	s_and_b64 vcc, vcc, s[46:47]
	v_cndmask_b32_e32 v59, v231, v59, vcc
	v_cmp_le_u32_e32 vcc, v123, v97
	v_cmp_gt_i32_e64 s[46:47], v122, v2
	s_and_b64 vcc, vcc, s[46:47]
	v_cndmask_b32_e32 v72, v231, v72, vcc
	v_cmp_le_u32_e32 vcc, v124, v97
	v_cmp_ge_i32_e64 s[46:47], v122, v2
	s_and_b64 vcc, vcc, s[46:47]
	v_cndmask_b32_e32 v73, v231, v73, vcc
	v_cmp_le_u32_e32 vcc, v126, v97
	v_cmp_gt_i32_e64 s[46:47], v125, v2
	s_and_b64 vcc, vcc, s[46:47]
	v_cndmask_b32_e32 v74, v231, v74, vcc
	v_cmp_le_u32_e32 vcc, v128, v97
	v_cmp_gt_i32_e64 s[46:47], v127, v2
	s_and_b64 vcc, vcc, s[46:47]
	v_cndmask_b32_e32 v75, v231, v75, vcc
	v_cmp_le_u32_e32 vcc, v130, v97
	v_cmp_gt_i32_e64 s[46:47], v129, v2
	s_and_b64 vcc, vcc, s[46:47]
	v_cndmask_b32_e32 v88, v231, v88, vcc
	v_cmp_le_u32_e32 vcc, v131, v97
	v_cmp_ge_i32_e64 s[46:47], v129, v2
	s_and_b64 vcc, vcc, s[46:47]
	v_cndmask_b32_e32 v89, v231, v89, vcc
	v_cmp_le_u32_e32 vcc, v133, v97
	v_cmp_gt_i32_e64 s[46:47], v132, v2
	s_and_b64 vcc, vcc, s[46:47]
	v_cndmask_b32_e32 v90, v231, v90, vcc
	v_cmp_le_u32_e32 vcc, v135, v97
	v_cmp_gt_i32_e64 s[46:47], v134, v2
	s_and_b64 vcc, vcc, s[46:47]
	v_cndmask_b32_e32 v91, v231, v91, vcc
	v_cmp_le_u32_e32 vcc, v137, v97
	v_cmp_gt_i32_e64 s[46:47], v136, v2
	s_and_b64 vcc, vcc, s[46:47]
	v_cndmask_b32_e32 v84, v231, v84, vcc
	v_cmp_le_u32_e32 vcc, v138, v97
	v_cmp_ge_i32_e64 s[46:47], v136, v2
	s_and_b64 vcc, vcc, s[46:47]
	v_cndmask_b32_e32 v85, v231, v85, vcc
	v_cmp_le_u32_e32 vcc, v140, v97
	v_cmp_gt_i32_e64 s[46:47], v139, v2
	s_and_b64 vcc, vcc, s[46:47]
	v_cndmask_b32_e32 v86, v231, v86, vcc
	v_cmp_le_u32_e32 vcc, v142, v97
	v_cmp_gt_i32_e64 s[46:47], v141, v2
	s_and_b64 vcc, vcc, s[46:47]
	v_cndmask_b32_e32 v87, v231, v87, vcc
	v_cmp_le_u32_e32 vcc, v144, v97
	v_cmp_gt_i32_e64 s[46:47], v143, v2
	s_and_b64 vcc, vcc, s[46:47]
	v_cndmask_b32_e32 v80, v231, v80, vcc
	v_cmp_le_u32_e32 vcc, v145, v97
	v_cmp_ge_i32_e64 s[46:47], v143, v2
	s_and_b64 vcc, vcc, s[46:47]
	v_cndmask_b32_e32 v81, v231, v81, vcc
	v_cmp_le_u32_e32 vcc, v147, v97
	v_cmp_gt_i32_e64 s[46:47], v146, v2
	s_and_b64 vcc, vcc, s[46:47]
	v_cndmask_b32_e32 v82, v231, v82, vcc
	v_cmp_le_u32_e32 vcc, v149, v97
	v_cmp_gt_i32_e64 s[46:47], v148, v2
	s_and_b64 vcc, vcc, s[46:47]
	v_cndmask_b32_e32 v83, v231, v83, vcc
	v_cmp_le_u32_e32 vcc, v151, v97
	v_cmp_gt_i32_e64 s[46:47], v150, v2
	s_and_b64 vcc, vcc, s[46:47]
	v_cndmask_b32_e32 v76, v231, v76, vcc
	v_cmp_le_u32_e32 vcc, v152, v97
	v_cmp_ge_i32_e64 s[46:47], v150, v2
	s_and_b64 vcc, vcc, s[46:47]
	v_cndmask_b32_e32 v77, v231, v77, vcc
	v_cmp_le_u32_e32 vcc, v154, v97
	v_cmp_gt_i32_e64 s[46:47], v153, v2
	s_and_b64 vcc, vcc, s[46:47]
	v_cndmask_b32_e32 v78, v231, v78, vcc
	v_cmp_le_u32_e32 vcc, v156, v97
	v_cmp_gt_i32_e64 s[46:47], v155, v2
	s_and_b64 vcc, vcc, s[46:47]
	v_cndmask_b32_e32 v79, v231, v79, vcc
	v_cmp_le_u32_e32 vcc, v158, v97
	v_cmp_gt_i32_e64 s[46:47], v157, v2
	s_and_b64 vcc, vcc, s[46:47]
	v_cndmask_b32_e32 v64, v231, v64, vcc
	v_cmp_le_u32_e32 vcc, v159, v97
	v_cmp_ge_i32_e64 s[46:47], v157, v2
	s_and_b64 vcc, vcc, s[46:47]
	v_cndmask_b32_e32 v65, v231, v65, vcc
	v_cmp_le_u32_e32 vcc, v161, v97
	v_cmp_gt_i32_e64 s[46:47], v160, v2
	s_and_b64 vcc, vcc, s[46:47]
	v_max3_f32 v200, v56, s10, v57
	v_cndmask_b32_e32 v66, v231, v66, vcc
	v_cmp_le_u32_e32 vcc, v163, v97
	v_cmp_gt_i32_e64 s[46:47], v162, v2
	v_max3_f32 v200, v200, v58, v59
	s_and_b64 vcc, vcc, s[46:47]
	v_max3_f32 v200, v200, v72, v73
	v_cndmask_b32_e32 v67, v231, v67, vcc
	v_cmp_le_u32_e32 vcc, v165, v97
	v_cmp_gt_i32_e64 s[46:47], v164, v2
	v_max3_f32 v200, v200, v74, v75
	s_and_b64 vcc, vcc, s[46:47]
	v_max3_f32 v200, v200, v88, v89
	v_cndmask_b32_e32 v68, v231, v68, vcc
	v_cmp_le_u32_e32 vcc, v166, v97
	v_cmp_ge_i32_e64 s[46:47], v164, v2
	v_max3_f32 v200, v200, v90, v91
	s_and_b64 vcc, vcc, s[46:47]
	v_max3_f32 v200, v200, v84, v85
	v_cndmask_b32_e32 v69, v231, v69, vcc
	v_cmp_le_u32_e32 vcc, v168, v97
	v_cmp_gt_i32_e64 s[46:47], v167, v2
	v_max3_f32 v200, v200, v86, v87
	s_and_b64 vcc, vcc, s[46:47]
	v_max3_f32 v200, v200, v80, v81
	v_cndmask_b32_e32 v70, v231, v70, vcc
	v_cmp_le_u32_e32 vcc, v170, v97
	v_cmp_gt_i32_e64 s[46:47], v169, v2
	v_max3_f32 v200, v200, v82, v83
	s_and_b64 vcc, vcc, s[46:47]
	v_max3_f32 v200, v200, v76, v77
	v_cndmask_b32_e32 v71, v231, v71, vcc
	v_cmp_le_u32_e32 vcc, v172, v97
	v_cmp_gt_i32_e64 s[46:47], v171, v2
	v_max3_f32 v200, v200, v78, v79
	s_and_b64 vcc, vcc, s[46:47]
	v_max3_f32 v200, v200, v64, v65
	v_cndmask_b32_e32 v60, v231, v60, vcc
	v_cmp_le_u32_e32 vcc, v173, v97
	v_cmp_ge_i32_e64 s[46:47], v171, v2
	v_max3_f32 v200, v200, v66, v67
	s_and_b64 vcc, vcc, s[46:47]
	v_max3_f32 v200, v200, v68, v69
	v_cndmask_b32_e32 v201, v231, v61, vcc
	v_cmp_le_u32_e32 vcc, v175, v97
	v_cmp_gt_i32_e64 s[46:47], v174, v2
	v_max3_f32 v200, v200, v70, v71
	s_and_b64 vcc, vcc, s[46:47]
	v_max3_f32 v61, v200, v60, v201
	v_cndmask_b32_e32 v200, v231, v62, vcc
	v_cmp_le_u32_e32 vcc, v177, v97
	v_cmp_gt_i32_e64 s[46:47], v176, v2
	s_and_b64 vcc, vcc, s[46:47]
	v_cndmask_b32_e32 v202, v231, v63, vcc
	v_cmp_le_u32_e32 vcc, v191, v97
	v_cmp_gt_i32_e64 s[46:47], v190, v2
	s_and_b64 vcc, vcc, s[46:47]
	v_cndmask_b32_e32 v203, v231, v52, vcc
	v_cmp_le_u32_e32 vcc, v192, v97
	v_cmp_ge_i32_e64 s[46:47], v190, v2
	s_and_b64 vcc, vcc, s[46:47]
	v_cndmask_b32_e32 v204, v231, v53, vcc
	v_cmp_le_u32_e32 vcc, v194, v97
	v_cmp_gt_i32_e64 s[46:47], v193, v2
	s_and_b64 vcc, vcc, s[46:47]
	v_cndmask_b32_e32 v205, v231, v54, vcc
	v_cmp_le_u32_e32 vcc, v196, v97
	v_cmp_gt_i32_e64 s[46:47], v195, v2
	v_max3_f32 v61, v61, v200, v202
	s_and_b64 vcc, vcc, s[46:47]
	v_max3_f32 v52, v61, v203, v204
	v_cndmask_b32_e32 v55, v231, v55, vcc
	v_and_b32_e32 v53, 64, v226
	v_max3_f32 v2, v52, v205, v55
.Lattn_mask_join:
	v_xor_b32_e32 v52, 16, v226
	v_add_u32_e32 v53, 64, v53
	v_cmp_lt_i32_e32 vcc, v52, v53
	v_sub_u32_e32 v62, 5, v0
	s_lshl_b32 s10, s8, 1
	v_cndmask_b32_e32 v52, v226, v52, vcc
	v_lshlrev_b32_e32 v54, 2, v52
	ds_bpermute_b32 v52, v54, v2
	s_add_i32 s10, s10, s12
	v_add_u32_e32 v3, v3, v103
	s_waitcnt lgkmcnt(0)
	v_max_f32_e32 v52, v52, v52
	v_max_f32_e32 v2, v2, v52
	v_xor_b32_e32 v52, 32, v226
	v_cmp_lt_i32_e32 vcc, v52, v53
	v_and_b32_e32 v53, 31, v99
	v_lshrrev_b32_e32 v53, v62, v53
	v_cndmask_b32_e32 v52, v226, v52, vcc
	v_lshlrev_b32_e32 v52, 2, v52
	ds_bpermute_b32 v61, v52, v2
	v_cmp_ne_u32_e32 vcc, 3, v98
	s_waitcnt lgkmcnt(0)
	v_max_f32_e32 v61, v61, v61
	v_max_f32_e32 v2, v2, v61
	v_sub_f32_e32 v62, v72, v2
	v_sub_f32_e32 v72, v74, v2
	v_sub_f32_e32 v74, v88, v2
	v_mul_f32_e32 v74, 0x3fb8aa3b, v74
	v_exp_f32_e32 v88, v74
	v_sub_f32_e32 v74, v89, v2
	v_mul_f32_e32 v74, 0x3fb8aa3b, v74
	v_exp_f32_e32 v89, v74
	v_sub_f32_e32 v74, v90, v2
	v_mul_f32_e32 v74, 0x3fb8aa3b, v74
	v_exp_f32_e32 v90, v74
	v_sub_f32_e32 v74, v91, v2
	v_sub_f32_e32 v56, v56, v2
	v_mul_f32_e32 v74, 0x3fb8aa3b, v74
	v_mul_f32_e32 v56, 0x3fb8aa3b, v56
	v_sub_f32_e32 v57, v57, v2
	v_exp_f32_e32 v91, v74
	v_sub_f32_e32 v74, v84, v2
	v_exp_f32_e32 v56, v56
	v_mul_f32_e32 v57, 0x3fb8aa3b, v57
	v_sub_f32_e32 v58, v58, v2
	v_mul_f32_e32 v74, 0x3fb8aa3b, v74
	v_exp_f32_e32 v57, v57
	v_mul_f32_e32 v58, 0x3fb8aa3b, v58
	v_sub_f32_e32 v59, v59, v2
	v_exp_f32_e32 v84, v74
	v_sub_f32_e32 v74, v85, v2
	v_exp_f32_e32 v58, v58
	v_mul_f32_e32 v59, 0x3fb8aa3b, v59
	v_mul_f32_e32 v74, 0x3fb8aa3b, v74
	v_exp_f32_e32 v59, v59
	v_mul_f32_e32 v62, 0x3fb8aa3b, v62
	v_sub_f32_e32 v63, v73, v2
	v_exp_f32_e32 v85, v74
	v_sub_f32_e32 v74, v86, v2
	v_add_f32_e32 v61, 0, v56
	v_exp_f32_e32 v62, v62
	v_mul_f32_e32 v63, 0x3fb8aa3b, v63
	v_mul_f32_e32 v74, 0x3fb8aa3b, v74
	v_add_f32_e32 v61, v57, v61
	v_exp_f32_e32 v63, v63
	v_mul_f32_e32 v72, 0x3fb8aa3b, v72
	v_sub_f32_e32 v73, v75, v2
	v_exp_f32_e32 v86, v74
	v_sub_f32_e32 v74, v87, v2
	v_add_f32_e32 v61, v58, v61
	v_exp_f32_e32 v72, v72
	v_mul_f32_e32 v73, 0x3fb8aa3b, v73
	v_mul_f32_e32 v74, 0x3fb8aa3b, v74
	v_add_f32_e32 v61, v59, v61
	v_exp_f32_e32 v73, v73
	v_exp_f32_e32 v87, v74
	v_sub_f32_e32 v74, v80, v2
	v_add_f32_e32 v61, v62, v61
	v_mul_f32_e32 v74, 0x3fb8aa3b, v74
	v_add_f32_e32 v61, v63, v61
	v_exp_f32_e32 v97, v74
	v_sub_f32_e32 v74, v81, v2
	v_add_f32_e32 v61, v72, v61
	v_mul_f32_e32 v74, 0x3fb8aa3b, v74
	v_add_f32_e32 v61, v73, v61
	v_exp_f32_e32 v206, v74
	v_sub_f32_e32 v74, v82, v2
	v_add_f32_e32 v61, v88, v61
	v_mul_f32_e32 v74, 0x3fb8aa3b, v74
	v_add_f32_e32 v61, v89, v61
	v_exp_f32_e32 v207, v74
	v_sub_f32_e32 v74, v83, v2
	v_add_f32_e32 v61, v90, v61
	v_mul_f32_e32 v74, 0x3fb8aa3b, v74
	v_add_f32_e32 v61, v91, v61
	v_exp_f32_e32 v208, v74
	v_sub_f32_e32 v74, v76, v2
	v_add_f32_e32 v61, v84, v61
	v_mul_f32_e32 v74, 0x3fb8aa3b, v74
	v_sub_f32_e32 v64, v64, v2
	v_add_f32_e32 v61, v85, v61
	v_exp_f32_e32 v209, v74
	v_sub_f32_e32 v74, v77, v2
	v_mul_f32_e32 v64, 0x3fb8aa3b, v64
	v_add_f32_e32 v61, v86, v61
	v_mul_f32_e32 v74, 0x3fb8aa3b, v74
	v_exp_f32_e32 v213, v64
	v_sub_f32_e32 v64, v65, v2
	v_add_f32_e32 v61, v87, v61
	v_exp_f32_e32 v210, v74
	v_sub_f32_e32 v74, v78, v2
	v_mul_f32_e32 v64, 0x3fb8aa3b, v64
	v_add_f32_e32 v61, v97, v61
	v_mul_f32_e32 v74, 0x3fb8aa3b, v74
	v_exp_f32_e32 v214, v64
	v_sub_f32_e32 v64, v66, v2
	v_add_f32_e32 v61, v206, v61
	v_exp_f32_e32 v211, v74
	v_sub_f32_e32 v74, v79, v2
	v_mul_f32_e32 v64, 0x3fb8aa3b, v64
	v_add_f32_e32 v61, v207, v61
	v_mul_f32_e32 v74, 0x3fb8aa3b, v74
	v_exp_f32_e32 v215, v64
	v_sub_f32_e32 v64, v67, v2
	v_add_f32_e32 v61, v208, v61
	v_exp_f32_e32 v212, v74
	v_mul_f32_e32 v64, 0x3fb8aa3b, v64
	v_add_f32_e32 v61, v209, v61
	v_exp_f32_e32 v216, v64
	v_sub_f32_e32 v64, v68, v2
	v_add_f32_e32 v61, v210, v61
	v_mul_f32_e32 v64, 0x3fb8aa3b, v64
	v_sub_f32_e32 v60, v60, v2
	v_add_f32_e32 v61, v211, v61
	v_exp_f32_e32 v217, v64
	v_sub_f32_e32 v64, v69, v2
	v_mul_f32_e32 v60, 0x3fb8aa3b, v60
	v_add_f32_e32 v61, v212, v61
	v_mul_f32_e32 v64, 0x3fb8aa3b, v64
	v_exp_f32_e32 v221, v60
	v_add_f32_e32 v61, v213, v61
	v_exp_f32_e32 v218, v64
	v_sub_f32_e32 v64, v70, v2
	v_add_f32_e32 v61, v214, v61
	v_mul_f32_e32 v64, 0x3fb8aa3b, v64
	v_add_f32_e32 v61, v215, v61
	v_exp_f32_e32 v219, v64
	v_cvt_pk_bf16_f32 v56, v56, v57
	v_add_f32_e32 v61, v216, v61
	v_add_f32_e32 v61, v217, v61
	v_cvt_pk_bf16_f32 v57, v58, v59
	v_add_f32_e32 v61, v218, v61
	v_lshl_add_u32 v74, v92, 1, s10
	v_and_b32_sdwa v64, v72, v225 dst_sel:DWORD dst_unused:UNUSED_PAD src0_sel:WORD_1 src1_sel:DWORD
	v_add_f32_e32 v76, v219, v61
	v_sub_f32_e32 v61, v71, v2
	v_cvt_pk_bf16_f32 v58, v62, v63
	v_and_b32_sdwa v59, v73, v225 dst_sel:DWORD dst_unused:UNUSED_PAD src0_sel:WORD_1 src1_sel:DWORD
	v_lshl_add_u32 v68, v197, 1, v74
	v_add3_u32 v69, v72, v64, s23
	v_lshl_add_u32 v72, v198, 1, v74
	v_mul_f32_e32 v61, 0x3fb8aa3b, v61
	v_add_u32_e32 v232, 0x9000, v68
	v_add_u32_e32 v233, 0xb000, v68
	v_add3_u32 v59, v73, v59, s23
	v_add_u32_e32 v234, 0xd000, v68
	v_add_u32_e32 v235, 0x9000, v72
	v_exp_f32_e32 v220, v61
	ds_read2_b64 v[60:63], v232 offset1:4
	ds_read2_b64 v[64:67], v233 offset0:32 offset1:36
	v_perm_b32 v59, v59, v69, s22
	ds_read2_b64 v[68:71], v234 offset0:64 offset1:68
	ds_read2_b64 v[72:75], v235 offset1:4
	v_add_f32_e32 v76, v220, v76
	v_add_f32_e32 v236, v221, v76
	v_sub_f32_e32 v76, v201, v2
	s_waitcnt lgkmcnt(0)
	v_mfma_f32_16x16x32_bf16 v[60:63], v[60:63], v[56:59], 0
	v_mul_f32_e32 v76, 0x3fb8aa3b, v76
	v_exp_f32_e32 v201, v76
	ds_read2_b64 v[76:79], v232 offset0:8 offset1:12
	v_mfma_f32_16x16x32_bf16 v[64:67], v[64:67], v[56:59], 0
	v_sub_f32_e32 v200, v200, v2
	ds_read2_b64 v[80:83], v233 offset0:40 offset1:44
	v_sub_f32_e32 v55, v55, v2
	v_mfma_f32_16x16x32_bf16 v[68:71], v[68:71], v[56:59], 0
	v_mul_f32_e32 v55, 0x3fb8aa3b, v55
	v_exp_f32_e32 v55, v55
	s_movk_i32 s10, 0x1000
	v_mfma_f32_16x16x32_bf16 v[56:59], v[72:75], v[56:59], 0
	v_cvt_pk_bf16_f32 v72, v88, v89
	v_cvt_pk_bf16_f32 v73, v90, v91
	v_cvt_pk_bf16_f32 v74, v84, v85
	v_cvt_pk_bf16_f32 v75, v86, v87
	ds_read2_b64 v[84:87], v234 offset0:72 offset1:76
	v_sub_f32_e32 v91, v203, v2
	s_waitcnt lgkmcnt(0)
	v_mfma_f32_16x16x32_bf16 v[60:63], v[76:79], v[72:75], v[60:63]
	v_mul_f32_e32 v76, 0x3fb8aa3b, v200
	v_exp_f32_e32 v88, v76
	ds_read2_b64 v[76:79], v235 offset0:8 offset1:12
	v_mfma_f32_16x16x32_bf16 v[64:67], v[80:83], v[72:75], v[64:67]
	v_add_f32_e32 v80, v201, v236
	v_add_f32_e32 v89, v88, v80
	v_sub_f32_e32 v80, v202, v2
	v_mfma_f32_16x16x32_bf16 v[68:71], v[84:87], v[72:75], v[68:71]
	v_mul_f32_e32 v80, 0x3fb8aa3b, v80
	s_waitcnt lgkmcnt(0)
	v_mfma_f32_16x16x32_bf16 v[56:59], v[76:79], v[72:75], v[56:59]
	ds_read2_b64 v[76:79], v232 offset0:16 offset1:20
	v_cvt_pk_bf16_f32 v72, v97, v206
	v_cvt_pk_bf16_f32 v73, v207, v208
	v_cvt_pk_bf16_f32 v74, v209, v210
	v_cvt_pk_bf16_f32 v75, v211, v212
	v_exp_f32_e32 v90, v80
	ds_read2_b64 v[80:83], v233 offset0:48 offset1:52
	s_waitcnt lgkmcnt(0)
	v_mfma_f32_16x16x32_bf16 v[60:63], v[76:79], v[72:75], v[60:63]
	v_mul_f32_e32 v76, 0x3fb8aa3b, v91
	ds_read2_b64 v[84:87], v234 offset0:80 offset1:84
	v_exp_f32_e32 v91, v76
	ds_read2_b64 v[76:79], v235 offset0:16 offset1:20
	v_mfma_f32_16x16x32_bf16 v[64:67], v[80:83], v[72:75], v[64:67]
	v_sub_f32_e32 v200, v205, v2
	v_add_f32_e32 v80, v90, v89
	v_add_f32_e32 v89, v91, v80
	s_waitcnt lgkmcnt(0)
	v_mfma_f32_16x16x32_bf16 v[68:71], v[84:87], v[72:75], v[68:71]
	v_sub_f32_e32 v80, v204, v2
	v_mfma_f32_16x16x32_bf16 v[56:59], v[76:79], v[72:75], v[56:59]
	ds_read2_b64 v[76:79], v232 offset0:24 offset1:28
	v_cvt_pk_bf16_f32 v72, v213, v214
	v_cvt_pk_bf16_f32 v73, v215, v216
	v_cvt_pk_bf16_f32 v74, v217, v218
	v_cvt_pk_bf16_f32 v75, v219, v220
	v_mul_f32_e32 v80, 0x3fb8aa3b, v80
	ds_read2_b64 v[84:87], v234 offset0:88 offset1:92
	s_waitcnt lgkmcnt(0)
	v_mfma_f32_16x16x32_bf16 v[60:63], v[76:79], v[72:75], v[60:63]
	v_mul_f32_e32 v76, 0x3fb8aa3b, v200
	v_exp_f32_e32 v200, v76
	ds_read2_b64 v[76:79], v235 offset0:24 offset1:28
	v_exp_f32_e32 v97, v80
	ds_read2_b64 v[80:83], v233 offset0:56 offset1:60
	s_waitcnt lgkmcnt(0)
	v_mfma_f32_16x16x32_bf16 v[76:79], v[76:79], v[72:75], v[56:59]
	s_nop 2
	v_mfma_f32_16x16x32_bf16 v[68:71], v[84:87], v[72:75], v[68:71]
	v_cvt_pk_bf16_f32 v84, v221, v201
	v_mfma_f32_16x16x32_bf16 v[80:83], v[80:83], v[72:75], v[64:67]
	v_cvt_pk_bf16_f32 v85, v88, v90
	v_add_f32_e32 v64, v97, v89
	v_add_f32_e32 v64, v200, v64
	v_add_f32_e32 v204, v55, v64
	ds_read2_b64 v[56:59], v232 offset0:32 offset1:36
	ds_read2_b64 v[72:75], v233 offset0:64 offset1:68
	v_cvt_pk_bf16_f32 v86, v91, v97
	v_and_b32_sdwa v65, v200, v225 dst_sel:DWORD dst_unused:UNUSED_PAD src0_sel:WORD_1 src1_sel:DWORD
	v_add3_u32 v65, v200, v65, s23
	ds_read2_b64 v[88:91], v234 offset0:96 offset1:100
	ds_read2_b64 v[200:203], v235 offset0:32 offset1:36
	ds_bpermute_b32 v54, v54, v204
	v_and_b32_sdwa v64, v55, v225 dst_sel:DWORD dst_unused:UNUSED_PAD src0_sel:WORD_1 src1_sel:DWORD
	v_add3_u32 v55, v55, v64, s23
	v_perm_b32 v87, v55, v65, s22
	v_lshlrev_b32_e32 v55, 4, v99
	v_and_or_b32 v53, v55, s10, v53
	s_waitcnt lgkmcnt(0)
	v_mfma_f32_16x16x32_bf16 v[64:67], v[56:59], v[84:87], v[60:63]
	v_mfma_f32_16x16x32_bf16 v[60:63], v[72:75], v[84:87], v[80:83]
	v_add_f32_e32 v73, v204, v54
	ds_bpermute_b32 v75, v52, v73
	v_lshl_add_u32 v72, v3, v0, v53
	v_mfma_f32_16x16x32_bf16 v[56:59], v[88:91], v[84:87], v[68:71]
	v_bfe_u32 v74, v99, 5, 3
	v_lshlrev_b32_e32 v0, 7, v74
	s_waitcnt lgkmcnt(0)
	v_add_f32_e32 v3, v73, v75
	v_mfma_f32_16x16x32_bf16 v[52:55], v[200:203], v[84:87], v[76:79]
	v_ashrrev_i32_e32 v73, 31, v72
	v_lshlrev_b32_e32 v70, 1, v92
	s_and_saveexec_b64 s[34:35], vcc
	s_xor_b64 s[46:47], exec, s[34:35]
	s_cbranch_execz .LBB0_1138
	v_ashrrev_i32_e32 v99, 31, v98
	v_lshlrev_b64 v[68:69], 13, v[98:99]
	v_lshl_add_u64 v[68:69], v[68:69], 0, v[72:73]
	v_lshlrev_b64 v[72:73], 10, v[68:69]
	v_lshl_add_u64 v[72:73], s[52:53], 0, v[72:73]
	v_lshl_add_u64 v[72:73], v[72:73], 0, v[0:1]
	v_bfe_u32 v0, v64, 16, 1
	v_add3_u32 v0, v64, v0, s23
	v_bfe_u32 v64, v65, 16, 1
	v_lshrrev_b32_e32 v0, 16, v0
	v_add3_u32 v64, v65, v64, s23
	v_and_or_b32 v64, v64, s15, v0
	v_cvt_pk_bf16_f32 v65, v66, v67
	v_bfe_u32 v0, v60, 16, 1
	v_add3_u32 v0, v60, v0, s23
	v_bfe_u32 v60, v61, 16, 1
	v_lshrrev_b32_e32 v0, 16, v0
	v_add3_u32 v60, v61, v60, s23
	v_and_or_b32 v60, v60, s15, v0
	v_cvt_pk_bf16_f32 v61, v62, v63
	v_bfe_u32 v0, v56, 16, 1
	v_add3_u32 v0, v56, v0, s23
	v_bfe_u32 v56, v57, 16, 1
	v_lshrrev_b32_e32 v0, 16, v0
	v_add3_u32 v56, v57, v56, s23
	v_and_or_b32 v56, v56, s15, v0
	v_cvt_pk_bf16_f32 v57, v58, v59
	v_bfe_u32 v0, v52, 16, 1
	v_add3_u32 v0, v52, v0, s23
	v_bfe_u32 v52, v53, 16, 1
	v_lshrrev_b32_e32 v0, 16, v0
	v_add3_u32 v52, v53, v52, s23
	v_and_or_b32 v52, v52, s15, v0
	v_mov_b32_e32 v71, v1
	v_lshl_add_u64 v[70:71], v[72:73], 0, v[70:71]
	v_cvt_pk_bf16_f32 v53, v54, v55
	flat_store_dwordx2 v[70:71], v[64:65] nt
	flat_store_dwordx2 v[70:71], v[60:61] offset:32 nt
	flat_store_dwordx2 v[70:71], v[56:57] offset:64 nt
	flat_store_dwordx2 v[70:71], v[52:53] offset:96 nt
	s_and_saveexec_b64 s[58:59], s[42:43]
	s_cbranch_execz .LBB0_1136
	v_lshlrev_b64 v[52:53], 6, v[68:69]
	v_lshl_add_u64 v[52:53], s[54:55], 0, v[52:53]
	v_lshlrev_b32_e32 v0, 3, v74
	v_lshl_add_u64 v[52:53], v[52:53], 0, v[0:1]
	flat_store_dwordx2 v[52:53], v[2:3]
